# GEMM units: first K-iteration peeled with MFMA SrcC=0, accumulator zeroing (128 v_mov per unit) removed
# speedup vs baseline: 1.0109x; 1.0109x over previous
; #define PG8_STAGE(bufoff, gbase, voff) do { _Pragma("unroll") for (int _i = 0; _i < 2; ++_i) \
;         __builtin_amdgcn_global_load_lds((const unsigned*)((const char*)(gbase) + (voff)[_i]), (PG8_LAS unsigned*)(lds + (bufoff) + ldsw + _i * 8192), 16, 0, 0); } while (0)
; #define PG8_LDA(dst, b, h) do { _Pragma("unroll") for (int m = 0; m < 4; ++m) _Pragma("unroll") for (int k = 0; k < 2; ++k) dst[m][k] = *(const PG8_LAS bf16x8*)(lds + PG8_SA(b, h) + aoff + m * 2048 + k * 1024); } while (0)
; #define PG8_LDB(dst, b, h) do { _Pragma("unroll") for (int n = 0; n < 2; ++n) _Pragma("unroll") for (int k = 0; k < 2; ++k) dst[n][k] = *(const PG8_LAS bf16x8*)(lds + PG8_SB(b, h) + boff + n * 2048 + k * 1024); } while (0)
; #define PG8_MMA(ai, bj, At, Bt) do { __builtin_amdgcn_s_setprio(1); _Pragma("unroll") for (int m = 0; m < 4; ++m) _Pragma("unroll") for (int n = 0; n < 2; ++n) _Pragma("unroll") for (int k = 0; k < 2; ++k) \
;         acc[ai][bj][m][n] = __builtin_amdgcn_mfma_f32_16x16x32_bf16(Bt[n][k], At[m][k], acc[ai][bj][m][n], 0, 0, 0); __builtin_amdgcn_s_setprio(0); } while (0)
; #define PG8_WAIT_V(n) asm volatile("s_waitcnt vmcnt(" #n ")" ::: "memory")
; #define PG8_WAIT_L(n) asm volatile("s_waitcnt lgkmcnt(" #n ")" ::: "memory")
; #define PG8_BAR __builtin_amdgcn_s_barrier()
; #define PG8_SCHED __builtin_amdgcn_sched_barrier(0)
; template <class Epi, class Sched, bool ALIGN_EPI = false, bool SP2 = false>
; __device__ __forceinline__ void gemm_phase(PG8_LAS unsigned char* lds, const Gemm g, const Sched& S, const Epi& E) {
;     ...
;             PG8_LDB(B0, 0, 0); PG8_LDB(B1, 0, 1); PG8_SCHED; PG8_LDA(At, 0, 0); PG8_STAGE(PG8_SA(1, 1), a1 + hstep, voffA);
;             PG8_WAIT_V(8); PG8_WAIT_L(0); PG8_BAR; PG8_MMA(0, 0, At, B0); PG8_MMA(0, 1, At, B1); PG8_BAR; PG8_SCHED;
;             PG8_LDA(At, 0, 1); PG8_STAGE(PG8_SB(0, 0), b2, voffB); PG8_STAGE(PG8_SB(0, 1), b2 + hstep, voffB); PG8_STAGE(PG8_SA(0, 0), a2, voffA);
.LBB0_232:
	s_add_u32 s20, s20, 0x80
	s_addc_u32 s21, s21, 0
	s_add_u32 s54, s22, 0x100
	s_addc_u32 s55, s23, 0
	s_mov_b32 s22, 0
	s_add_i32 s56, s22, 2
	s_add_u32 s57, s20, 0x80
	s_addc_u32 s23, s21, 0
	s_add_i32 s64, 0, 0x10000
	s_cmp_eq_u32 s43, s22
	s_cselect_b32 s23, s9, s23
	s_cselect_b32 s22, s8, s57
	v_add_u32_e32 v175, s64, v172
	s_cselect_b32 s59, s19, s55
	s_cselect_b32 s58, s18, s54
	s_add_i32 s57, 0, 0x14000
	ds_read_b128 v[176:179], v175
	ds_read_b128 v[180:183], v175 offset:1024
	ds_read_b128 v[184:187], v175 offset:2048
	ds_read_b128 v[188:191], v175 offset:3072
	v_add_u32_e32 v175, s57, v172
	ds_read_b128 v[192:195], v175
	ds_read_b128 v[196:199], v175 offset:1024
	ds_read_b128 v[200:203], v175 offset:2048
	ds_read_b128 v[204:207], v175 offset:3072
	v_lshl_add_u64 v[240:241], s[20:21], 0, v[150:151]
	s_add_i32 m0, s35, 0xc000
	ds_read_b128 v[208:211], v174
	ds_read_b128 v[212:215], v174 offset:1024
	ds_read_b128 v[216:219], v174 offset:2048
	ds_read_b128 v[220:223], v174 offset:3072
	ds_read_b128 v[224:227], v174 offset:4096
	ds_read_b128 v[228:231], v174 offset:5120
	ds_read_b128 v[232:235], v174 offset:6144
	ds_read_b128 v[236:239], v174 offset:7168
	global_load_lds_dwordx4 v[240:241], off
	v_lshl_add_u64 v[240:241], s[20:21], 0, v[152:153]
	s_add_i32 m0, s35, 0xe000
	s_nop 0
	global_load_lds_dwordx4 v[240:241], off
	s_waitcnt vmcnt(8)
	s_waitcnt lgkmcnt(0)
	s_barrier
	s_setprio 1
	s_waitcnt lgkmcnt(0)
	v_mfma_f32_16x16x32_bf16 v[126:129], v[176:179], v[208:211], 0
	v_mfma_f32_16x16x32_bf16 v[122:125], v[184:187], v[208:211], 0
	v_mfma_f32_16x16x32_bf16 v[118:121], v[176:179], v[216:219], 0
	v_mfma_f32_16x16x32_bf16 v[114:117], v[184:187], v[216:219], 0
	v_mfma_f32_16x16x32_bf16 v[102:105], v[176:179], v[224:227], 0
	v_mfma_f32_16x16x32_bf16 v[98:101], v[184:187], v[224:227], 0
	v_mfma_f32_16x16x32_bf16 v[86:89], v[176:179], v[232:235], 0
	v_mfma_f32_16x16x32_bf16 v[82:85], v[184:187], v[232:235], 0
	v_mfma_f32_16x16x32_bf16 v[126:129], v[180:183], v[212:215], v[126:129]
	v_mfma_f32_16x16x32_bf16 v[122:125], v[188:191], v[212:215], v[122:125]
	v_mfma_f32_16x16x32_bf16 v[118:121], v[180:183], v[220:223], v[118:121]
	v_mfma_f32_16x16x32_bf16 v[114:117], v[188:191], v[220:223], v[114:117]
	v_mfma_f32_16x16x32_bf16 v[102:105], v[180:183], v[228:231], v[102:105]
	v_mfma_f32_16x16x32_bf16 v[98:101], v[188:191], v[228:231], v[98:101]
	v_mfma_f32_16x16x32_bf16 v[86:89], v[180:183], v[236:239], v[86:89]
	v_mfma_f32_16x16x32_bf16 v[82:85], v[188:191], v[236:239], v[82:85]
	s_setprio 0
	s_setprio 1
	v_mfma_f32_16x16x32_bf16 v[110:113], v[192:195], v[208:211], 0
	v_mfma_f32_16x16x32_bf16 v[106:109], v[200:203], v[208:211], 0
	v_mfma_f32_16x16x32_bf16 v[94:97], v[192:195], v[216:219], 0
	v_mfma_f32_16x16x32_bf16 v[90:93], v[200:203], v[216:219], 0
	v_mfma_f32_16x16x32_bf16 v[78:81], v[192:195], v[224:227], 0
	v_mfma_f32_16x16x32_bf16 v[74:77], v[200:203], v[224:227], 0
	v_mfma_f32_16x16x32_bf16 v[70:73], v[192:195], v[232:235], 0
	v_mfma_f32_16x16x32_bf16 v[66:69], v[200:203], v[232:235], 0
	v_mfma_f32_16x16x32_bf16 v[110:113], v[196:199], v[212:215], v[110:113]
	v_mfma_f32_16x16x32_bf16 v[106:109], v[204:207], v[212:215], v[106:109]
	v_mfma_f32_16x16x32_bf16 v[94:97], v[196:199], v[220:223], v[94:97]
	v_mfma_f32_16x16x32_bf16 v[90:93], v[204:207], v[220:223], v[90:93]
	v_mfma_f32_16x16x32_bf16 v[78:81], v[196:199], v[228:231], v[78:81]
	v_mfma_f32_16x16x32_bf16 v[74:77], v[204:207], v[228:231], v[74:77]
	v_mfma_f32_16x16x32_bf16 v[70:73], v[196:199], v[236:239], v[70:73]
	v_mfma_f32_16x16x32_bf16 v[66:69], v[204:207], v[236:239], v[66:69]
	s_setprio 0
	s_barrier
	s_add_i32 s64, s64, s28
	v_lshl_add_u64 v[240:241], s[58:59], 0, v[0:1]
	s_mov_b32 m0, s64
	ds_read_b128 v[208:211], v174 offset:16384
	ds_read_b128 v[212:215], v174 offset:17408
	ds_read_b128 v[216:219], v174 offset:18432
	ds_read_b128 v[220:223], v174 offset:19456
	ds_read_b128 v[224:227], v174 offset:20480
	ds_read_b128 v[228:231], v174 offset:21504
	ds_read_b128 v[232:235], v174 offset:22528
	ds_read_b128 v[236:239], v174 offset:23552
	global_load_lds_dwordx4 v[240:241], off
	s_add_i32 m0, s64, 0x2000
	v_lshl_add_u64 v[242:243], s[58:59], 0, v[144:145]
	s_add_u32 s58, s58, s62
	s_addc_u32 s59, s59, 0
	s_add_i32 s57, s57, s28
	global_load_lds_dwordx4 v[242:243], off
	v_lshl_add_u64 v[244:245], s[58:59], 0, v[0:1]
	s_mov_b32 m0, s57
	v_lshl_add_u64 v[246:247], s[58:59], 0, v[144:145]
	global_load_lds_dwordx4 v[244:245], off
	s_add_i32 m0, s57, 0x2000
	v_lshl_add_u64 v[248:249], s[22:23], 0, v[148:149]
	global_load_lds_dwordx4 v[246:247], off
	s_mov_b32 m0, s35
	v_lshl_add_u64 v[250:251], s[22:23], 0, v[146:147]
	global_load_lds_dwordx4 v[248:249], off
	s_mov_b32 m0, s36
	s_nop 0
	global_load_lds_dwordx4 v[250:251], off
	s_waitcnt vmcnt(8)
	s_waitcnt lgkmcnt(0)
	s_barrier
; #define PG8_STAGE(bufoff, gbase, voff) do { _Pragma("unroll") for (int _i = 0; _i < 2; ++_i) \
;         __builtin_amdgcn_global_load_lds((const unsigned*)((const char*)(gbase) + (voff)[_i]), (PG8_LAS unsigned*)(lds + (bufoff) + ldsw + _i * 8192), 16, 0, 0); } while (0)
; #define PG8_LDA(dst, b, h) do { _Pragma("unroll") for (int m = 0; m < 4; ++m) _Pragma("unroll") for (int k = 0; k < 2; ++k) dst[m][k] = *(const PG8_LAS bf16x8*)(lds + PG8_SA(b, h) + aoff + m * 2048 + k * 1024); } while (0)
; #define PG8_LDB(dst, b, h) do { _Pragma("unroll") for (int n = 0; n < 2; ++n) _Pragma("unroll") for (int k = 0; k < 2; ++k) dst[n][k] = *(const PG8_LAS bf16x8*)(lds + PG8_SB(b, h) + boff + n * 2048 + k * 1024); } while (0)
; #define PG8_MMA(ai, bj, At, Bt) do { __builtin_amdgcn_s_setprio(1); _Pragma("unroll") for (int m = 0; m < 4; ++m) _Pragma("unroll") for (int n = 0; n < 2; ++n) _Pragma("unroll") for (int k = 0; k < 2; ++k) \
;         acc[ai][bj][m][n] = __builtin_amdgcn_mfma_f32_16x16x32_bf16(Bt[n][k], At[m][k], acc[ai][bj][m][n], 0, 0, 0); __builtin_amdgcn_s_setprio(0); } while (0)
; #define PG8_WAIT_V(n) asm volatile("s_waitcnt vmcnt(" #n ")" ::: "memory")
; #define PG8_WAIT_L(n) asm volatile("s_waitcnt lgkmcnt(" #n ")" ::: "memory")
; #define PG8_BAR __builtin_amdgcn_s_barrier()
; #define PG8_SCHED __builtin_amdgcn_sched_barrier(0)
; template <class Epi, class Sched, bool ALIGN_EPI = false, bool SP2 = false>
; __device__ __forceinline__ void gemm_phase(PG8_LAS unsigned char* lds, const Gemm g, const Sched& S, const Epi& E) {
;     ...
;             PG8_WAIT_V(8); PG8_WAIT_L(0); PG8_BAR; PG8_MMA(0, 0, At, B0); PG8_MMA(0, 1, At, B1); PG8_BAR; PG8_SCHED;
;             PG8_LDA(At, 0, 1); PG8_STAGE(PG8_SB(0, 0), b2, voffB); PG8_STAGE(PG8_SB(0, 1), b2 + hstep, voffB); PG8_STAGE(PG8_SA(0, 0), a2, voffA);
;             PG8_WAIT_V(8); PG8_WAIT_L(0); PG8_BAR; PG8_MMA(1, 0, At, B0); PG8_MMA(1, 1, At, B1); PG8_BAR; PG8_SCHED;
;             PG8_LDB(B0, 1, 0); PG8_LDB(B1, 1, 1); PG8_SCHED; PG8_LDA(At, 1, 0); PG8_STAGE(PG8_SA(0, 1), a2 + hstep, voffA);
;             PG8_WAIT_V(8); PG8_WAIT_L(0); PG8_BAR; PG8_MMA(0, 0, At, B0); PG8_MMA(0, 1, At, B1); PG8_BAR; PG8_SCHED;
	s_setprio 1
	s_waitcnt lgkmcnt(0)
	v_mfma_f32_16x16x32_bf16 v[62:65], v[176:179], v[208:211], 0
	v_mfma_f32_16x16x32_bf16 v[58:61], v[184:187], v[208:211], 0
	v_mfma_f32_16x16x32_bf16 v[54:57], v[176:179], v[216:219], 0
	v_mfma_f32_16x16x32_bf16 v[50:53], v[184:187], v[216:219], 0
	v_mfma_f32_16x16x32_bf16 v[38:41], v[176:179], v[224:227], 0
	v_mfma_f32_16x16x32_bf16 v[34:37], v[184:187], v[224:227], 0
	v_mfma_f32_16x16x32_bf16 v[22:25], v[176:179], v[232:235], 0
	v_mfma_f32_16x16x32_bf16 v[18:21], v[184:187], v[232:235], 0
	v_mfma_f32_16x16x32_bf16 v[62:65], v[180:183], v[212:215], v[62:65]
	v_mfma_f32_16x16x32_bf16 v[58:61], v[188:191], v[212:215], v[58:61]
	v_mfma_f32_16x16x32_bf16 v[54:57], v[180:183], v[220:223], v[54:57]
	v_mfma_f32_16x16x32_bf16 v[50:53], v[188:191], v[220:223], v[50:53]
	v_mfma_f32_16x16x32_bf16 v[38:41], v[180:183], v[228:231], v[38:41]
	v_mfma_f32_16x16x32_bf16 v[34:37], v[188:191], v[228:231], v[34:37]
	v_mfma_f32_16x16x32_bf16 v[22:25], v[180:183], v[236:239], v[22:25]
	v_mfma_f32_16x16x32_bf16 v[18:21], v[188:191], v[236:239], v[18:21]
	s_setprio 0
	s_setprio 1
	v_mfma_f32_16x16x32_bf16 v[46:49], v[192:195], v[208:211], 0
	v_mfma_f32_16x16x32_bf16 v[42:45], v[200:203], v[208:211], 0
	v_mfma_f32_16x16x32_bf16 v[30:33], v[192:195], v[216:219], 0
	v_mfma_f32_16x16x32_bf16 v[26:29], v[200:203], v[216:219], 0
	v_mfma_f32_16x16x32_bf16 v[14:17], v[192:195], v[224:227], 0
	v_mfma_f32_16x16x32_bf16 v[10:13], v[200:203], v[224:227], 0
	v_mfma_f32_16x16x32_bf16 v[6:9], v[192:195], v[232:235], 0
	v_mfma_f32_16x16x32_bf16 v[2:5], v[200:203], v[232:235], 0
	v_mfma_f32_16x16x32_bf16 v[46:49], v[196:199], v[212:215], v[46:49]
	v_mfma_f32_16x16x32_bf16 v[42:45], v[204:207], v[212:215], v[42:45]
	v_mfma_f32_16x16x32_bf16 v[30:33], v[196:199], v[220:223], v[30:33]
	v_mfma_f32_16x16x32_bf16 v[26:29], v[204:207], v[220:223], v[26:29]
	v_mfma_f32_16x16x32_bf16 v[14:17], v[196:199], v[228:231], v[14:17]
	v_mfma_f32_16x16x32_bf16 v[10:13], v[204:207], v[228:231], v[10:13]
	v_mfma_f32_16x16x32_bf16 v[6:9], v[196:199], v[236:239], v[6:9]
	v_mfma_f32_16x16x32_bf16 v[2:5], v[204:207], v[236:239], v[2:5]
	s_setprio 0
	s_barrier
	s_add_i32 s57, 0, 0x18000
	v_add_u32_e32 v175, s57, v172
	s_add_i32 s58, 0, 0x1c000
	ds_read_b128 v[176:179], v175
	ds_read_b128 v[180:183], v175 offset:1024
	ds_read_b128 v[184:187], v175 offset:2048
	ds_read_b128 v[188:191], v175 offset:3072
	v_add_u32_e32 v175, s58, v172
	ds_read_b128 v[192:195], v175
	ds_read_b128 v[196:199], v175 offset:1024
	ds_read_b128 v[200:203], v175 offset:2048
	ds_read_b128 v[204:207], v175 offset:3072
	s_add_u32 s22, s22, s62
	s_addc_u32 s23, s23, 0
	s_mov_b32 m0, s37
	v_lshl_add_u64 v[252:253], s[22:23], 0, v[148:149]
	ds_read_b128 v[208:211], v174 offset:32768
	ds_read_b128 v[212:215], v174 offset:33792
	ds_read_b128 v[216:219], v174 offset:34816
	ds_read_b128 v[220:223], v174 offset:35840
	ds_read_b128 v[224:227], v174 offset:36864
	ds_read_b128 v[228:231], v174 offset:37888
	ds_read_b128 v[232:235], v174 offset:38912
	ds_read_b128 v[236:239], v174 offset:39936
	global_load_lds_dwordx4 v[252:253], off
	v_lshl_add_u64 v[252:253], s[22:23], 0, v[146:147]
	s_mov_b32 m0, s38
	s_nop 0
	global_load_lds_dwordx4 v[252:253], off
	s_waitcnt vmcnt(8)
	s_waitcnt lgkmcnt(0)
	s_barrier
	s_setprio 1
	s_waitcnt lgkmcnt(0)
	v_mfma_f32_16x16x32_bf16 v[126:129], v[176:179], v[208:211], v[126:129]
	v_mfma_f32_16x16x32_bf16 v[122:125], v[184:187], v[208:211], v[122:125]
	v_mfma_f32_16x16x32_bf16 v[118:121], v[176:179], v[216:219], v[118:121]
	v_mfma_f32_16x16x32_bf16 v[114:117], v[184:187], v[216:219], v[114:117]
	v_mfma_f32_16x16x32_bf16 v[102:105], v[176:179], v[224:227], v[102:105]
	v_mfma_f32_16x16x32_bf16 v[98:101], v[184:187], v[224:227], v[98:101]
	v_mfma_f32_16x16x32_bf16 v[86:89], v[176:179], v[232:235], v[86:89]
	v_mfma_f32_16x16x32_bf16 v[82:85], v[184:187], v[232:235], v[82:85]
	v_mfma_f32_16x16x32_bf16 v[126:129], v[180:183], v[212:215], v[126:129]
	v_mfma_f32_16x16x32_bf16 v[122:125], v[188:191], v[212:215], v[122:125]
	v_mfma_f32_16x16x32_bf16 v[118:121], v[180:183], v[220:223], v[118:121]
	v_mfma_f32_16x16x32_bf16 v[114:117], v[188:191], v[220:223], v[114:117]
	v_mfma_f32_16x16x32_bf16 v[102:105], v[180:183], v[228:231], v[102:105]
	v_mfma_f32_16x16x32_bf16 v[98:101], v[188:191], v[228:231], v[98:101]
	v_mfma_f32_16x16x32_bf16 v[86:89], v[180:183], v[236:239], v[86:89]
	v_mfma_f32_16x16x32_bf16 v[82:85], v[188:191], v[236:239], v[82:85]
	s_setprio 0
	s_setprio 1
	v_mfma_f32_16x16x32_bf16 v[110:113], v[192:195], v[208:211], v[110:113]
	v_mfma_f32_16x16x32_bf16 v[106:109], v[200:203], v[208:211], v[106:109]
	v_mfma_f32_16x16x32_bf16 v[94:97], v[192:195], v[216:219], v[94:97]
	v_mfma_f32_16x16x32_bf16 v[90:93], v[200:203], v[216:219], v[90:93]
	v_mfma_f32_16x16x32_bf16 v[78:81], v[192:195], v[224:227], v[78:81]
	v_mfma_f32_16x16x32_bf16 v[74:77], v[200:203], v[224:227], v[74:77]
	v_mfma_f32_16x16x32_bf16 v[70:73], v[192:195], v[232:235], v[70:73]
	v_mfma_f32_16x16x32_bf16 v[66:69], v[200:203], v[232:235], v[66:69]
	v_mfma_f32_16x16x32_bf16 v[110:113], v[196:199], v[212:215], v[110:113]
	v_mfma_f32_16x16x32_bf16 v[106:109], v[204:207], v[212:215], v[106:109]
	v_mfma_f32_16x16x32_bf16 v[94:97], v[196:199], v[220:223], v[94:97]
	v_mfma_f32_16x16x32_bf16 v[90:93], v[204:207], v[220:223], v[90:93]
	v_mfma_f32_16x16x32_bf16 v[78:81], v[196:199], v[228:231], v[78:81]
	v_mfma_f32_16x16x32_bf16 v[74:77], v[204:207], v[228:231], v[74:77]
	v_mfma_f32_16x16x32_bf16 v[70:73], v[196:199], v[236:239], v[70:73]
	v_mfma_f32_16x16x32_bf16 v[66:69], v[204:207], v[236:239], v[66:69]
	s_setprio 0
	s_barrier
; #define PG8_STAGE(bufoff, gbase, voff) do { _Pragma("unroll") for (int _i = 0; _i < 2; ++_i) \
;         __builtin_amdgcn_global_load_lds((const unsigned*)((const char*)(gbase) + (voff)[_i]), (PG8_LAS unsigned*)(lds + (bufoff) + ldsw + _i * 8192), 16, 0, 0); } while (0)
; #define PG8_LDA(dst, b, h) do { _Pragma("unroll") for (int m = 0; m < 4; ++m) _Pragma("unroll") for (int k = 0; k < 2; ++k) dst[m][k] = *(const PG8_LAS bf16x8*)(lds + PG8_SA(b, h) + aoff + m * 2048 + k * 1024); } while (0)
; #define PG8_MMA(ai, bj, At, Bt) do { __builtin_amdgcn_s_setprio(1); _Pragma("unroll") for (int m = 0; m < 4; ++m) _Pragma("unroll") for (int n = 0; n < 2; ++n) _Pragma("unroll") for (int k = 0; k < 2; ++k) \
;         acc[ai][bj][m][n] = __builtin_amdgcn_mfma_f32_16x16x32_bf16(Bt[n][k], At[m][k], acc[ai][bj][m][n], 0, 0, 0); __builtin_amdgcn_s_setprio(0); } while (0)
; #define PG8_WAIT_V(n) asm volatile("s_waitcnt vmcnt(" #n ")" ::: "memory")
; #define PG8_WAIT_L(n) asm volatile("s_waitcnt lgkmcnt(" #n ")" ::: "memory")
; #define PG8_BAR __builtin_amdgcn_s_barrier()
; #define PG8_SCHED __builtin_amdgcn_sched_barrier(0)
; template <class Epi, class Sched, bool ALIGN_EPI = false, bool SP2 = false>
; __device__ __forceinline__ void gemm_phase(PG8_LAS unsigned char* lds, const Gemm g, const Sched& S, const Epi& E) {
;     ...
;             PG8_WAIT_V(8); PG8_WAIT_L(0); PG8_BAR; PG8_MMA(0, 0, At, B0); PG8_MMA(0, 1, At, B1); PG8_BAR; PG8_SCHED;
;             PG8_LDA(At, 1, 1); PG8_STAGE(PG8_SB(1, 0), b3, voffB); PG8_STAGE(PG8_SB(1, 1), b3 + hstep, voffB); PG8_STAGE(PG8_SA(1, 0), a3, voffA);
;             PG8_WAIT_V(8); PG8_WAIT_L(0); PG8_BAR; PG8_MMA(1, 0, At, B0); PG8_MMA(1, 1, At, B1); PG8_BAR; PG8_SCHED;
	s_add_i32 s22, s57, s28
	v_lshl_add_u64 v[240:241], v[240:241], 0, s[86:87]
	s_mov_b32 m0, s22
	ds_read_b128 v[208:211], v174 offset:49152
	ds_read_b128 v[212:215], v174 offset:50176
	ds_read_b128 v[216:219], v174 offset:51200
	ds_read_b128 v[220:223], v174 offset:52224
	ds_read_b128 v[224:227], v174 offset:53248
	ds_read_b128 v[228:231], v174 offset:54272
	ds_read_b128 v[232:235], v174 offset:55296
	ds_read_b128 v[236:239], v174 offset:56320
	global_load_lds_dwordx4 v[240:241], off
	v_lshl_add_u64 v[240:241], v[242:243], 0, s[86:87]
	s_add_i32 m0, s22, 0x2000
	s_add_i32 s22, s58, s28
	global_load_lds_dwordx4 v[240:241], off
	v_lshl_add_u64 v[240:241], v[244:245], 0, s[86:87]
	s_mov_b32 m0, s22
	s_nop 0
	global_load_lds_dwordx4 v[240:241], off
	v_lshl_add_u64 v[240:241], v[246:247], 0, s[86:87]
	s_add_i32 m0, s22, 0x2000
	s_nop 0
	global_load_lds_dwordx4 v[240:241], off
	v_lshl_add_u64 v[240:241], v[248:249], 0, s[86:87]
	s_mov_b32 m0, s40
	s_nop 0
	global_load_lds_dwordx4 v[240:241], off
	v_lshl_add_u64 v[240:241], v[250:251], 0, s[86:87]
	s_mov_b32 m0, s41
	s_nop 0
	global_load_lds_dwordx4 v[240:241], off
	s_waitcnt vmcnt(8)
	s_waitcnt lgkmcnt(0)
	s_barrier
	s_setprio 1
	s_waitcnt lgkmcnt(0)
	v_mfma_f32_16x16x32_bf16 v[62:65], v[176:179], v[208:211], v[62:65]
	v_mfma_f32_16x16x32_bf16 v[58:61], v[184:187], v[208:211], v[58:61]
	v_mfma_f32_16x16x32_bf16 v[54:57], v[176:179], v[216:219], v[54:57]
	v_mfma_f32_16x16x32_bf16 v[50:53], v[184:187], v[216:219], v[50:53]
	v_mfma_f32_16x16x32_bf16 v[38:41], v[176:179], v[224:227], v[38:41]
	v_mfma_f32_16x16x32_bf16 v[34:37], v[184:187], v[224:227], v[34:37]
	v_mfma_f32_16x16x32_bf16 v[22:25], v[176:179], v[232:235], v[22:25]
	v_mfma_f32_16x16x32_bf16 v[18:21], v[184:187], v[232:235], v[18:21]
	v_mfma_f32_16x16x32_bf16 v[62:65], v[180:183], v[212:215], v[62:65]
	v_mfma_f32_16x16x32_bf16 v[58:61], v[188:191], v[212:215], v[58:61]
	v_mfma_f32_16x16x32_bf16 v[54:57], v[180:183], v[220:223], v[54:57]
	v_mfma_f32_16x16x32_bf16 v[50:53], v[188:191], v[220:223], v[50:53]
	v_mfma_f32_16x16x32_bf16 v[38:41], v[180:183], v[228:231], v[38:41]
	v_mfma_f32_16x16x32_bf16 v[34:37], v[188:191], v[228:231], v[34:37]
	v_mfma_f32_16x16x32_bf16 v[22:25], v[180:183], v[236:239], v[22:25]
	v_mfma_f32_16x16x32_bf16 v[18:21], v[188:191], v[236:239], v[18:21]
	s_setprio 0
	s_setprio 1
	v_mfma_f32_16x16x32_bf16 v[46:49], v[192:195], v[208:211], v[46:49]
	v_mfma_f32_16x16x32_bf16 v[42:45], v[200:203], v[208:211], v[42:45]
	v_mfma_f32_16x16x32_bf16 v[30:33], v[192:195], v[216:219], v[30:33]
	v_mfma_f32_16x16x32_bf16 v[26:29], v[200:203], v[216:219], v[26:29]
	v_mfma_f32_16x16x32_bf16 v[14:17], v[192:195], v[224:227], v[14:17]
	v_mfma_f32_16x16x32_bf16 v[10:13], v[200:203], v[224:227], v[10:13]
	v_mfma_f32_16x16x32_bf16 v[6:9], v[192:195], v[232:235], v[6:9]
	v_mfma_f32_16x16x32_bf16 v[2:5], v[200:203], v[232:235], v[2:5]
	v_mfma_f32_16x16x32_bf16 v[46:49], v[196:199], v[212:215], v[46:49]
	v_mfma_f32_16x16x32_bf16 v[42:45], v[204:207], v[212:215], v[42:45]
	v_mfma_f32_16x16x32_bf16 v[30:33], v[196:199], v[220:223], v[30:33]
	v_mfma_f32_16x16x32_bf16 v[26:29], v[204:207], v[220:223], v[26:29]
	v_mfma_f32_16x16x32_bf16 v[14:17], v[196:199], v[228:231], v[14:17]
	v_mfma_f32_16x16x32_bf16 v[10:13], v[204:207], v[228:231], v[10:13]
	v_mfma_f32_16x16x32_bf16 v[6:9], v[196:199], v[236:239], v[6:9]
	v_mfma_f32_16x16x32_bf16 v[2:5], v[204:207], v[236:239], v[2:5]
	s_setprio 0
	s_barrier
	s_add_u32 s20, s20, 0x100
	s_addc_u32 s21, s21, 0
	s_add_u32 s54, s54, 0x100
	s_addc_u32 s55, s55, 0
	s_cmp_ge_u32 s56, s39
	s_mov_b32 s22, s56
	s_cbranch_scc1 .Lpeel_after_A

; #define PG8_BAR __builtin_amdgcn_s_barrier()
; template <class Epi, class Sched, bool ALIGN_EPI = false, bool SP2 = false>
; __device__ __forceinline__ void gemm_phase(PG8_LAS unsigned char* lds, const Gemm g, const Sched& S, const Epi& E) {
;     ...
;         }
;         if constexpr (ALIGN_EPI) { if (wr == 0) PG8_BAR; }
.Lpeel_after_A:
	s_and_b64 vcc, exec, s[16:17]
	s_cbranch_vccz .LBB0_236
	s_barrier

; #define PG8_STAGE(bufoff, gbase, voff) do { _Pragma("unroll") for (int _i = 0; _i < 2; ++_i) \
;         __builtin_amdgcn_global_load_lds((const unsigned*)((const char*)(gbase) + (voff)[_i]), (PG8_LAS unsigned*)(lds + (bufoff) + ldsw + _i * 8192), 16, 0, 0); } while (0)
; #define PG8_LDA(dst, b, h) do { _Pragma("unroll") for (int m = 0; m < 4; ++m) _Pragma("unroll") for (int k = 0; k < 2; ++k) dst[m][k] = *(const PG8_LAS bf16x8*)(lds + PG8_SA(b, h) + aoff + m * 2048 + k * 1024); } while (0)
; #define PG8_LDB(dst, b, h) do { _Pragma("unroll") for (int n = 0; n < 2; ++n) _Pragma("unroll") for (int k = 0; k < 2; ++k) dst[n][k] = *(const PG8_LAS bf16x8*)(lds + PG8_SB(b, h) + boff + n * 2048 + k * 1024); } while (0)
; #define PG8_MMA(ai, bj, At, Bt) do { __builtin_amdgcn_s_setprio(1); _Pragma("unroll") for (int m = 0; m < 4; ++m) _Pragma("unroll") for (int n = 0; n < 2; ++n) _Pragma("unroll") for (int k = 0; k < 2; ++k) \
;         acc[ai][bj][m][n] = __builtin_amdgcn_mfma_f32_16x16x32_bf16(Bt[n][k], At[m][k], acc[ai][bj][m][n], 0, 0, 0); __builtin_amdgcn_s_setprio(0); } while (0)
; #define PG8_WAIT_V(n) asm volatile("s_waitcnt vmcnt(" #n ")" ::: "memory")
; #define PG8_WAIT_L(n) asm volatile("s_waitcnt lgkmcnt(" #n ")" ::: "memory")
; #define PG8_BAR __builtin_amdgcn_s_barrier()
; #define PG8_SCHED __builtin_amdgcn_sched_barrier(0)
; template <class Epi, class Sched, bool ALIGN_EPI = false, bool SP2 = false>
; __device__ __forceinline__ void gemm_phase(PG8_LAS unsigned char* lds, const Gemm g, const Sched& S, const Epi& E) {
;     ...
;         for (int t = 0; t < nt; t += 2) {
;             const bool last = (t == nt - 2);
;             const char* a1 = cA + (size_t)(t + 1) * kstep;
;             const char* a2 = last ? nA : cA + (size_t)(t + 2) * kstep; const char* b2 = last ? nB : cB + (size_t)(t + 2) * kstep;
;             const char* a3 = a2 + kstep; const char* b3 = b2 + kstep;
;             if (last && has_next) S.a_ready(nxt);
;             if constexpr (SP2) {
;             PG8_LDB(B0, 0, 0); PG8_LDB(B1, 0, 1); PG8_SCHED; PG8_LDA(At, 0, 0); PG8_STAGE(PG8_SA(1, 1), a1 + hstep, voffA);
;             PG8_WAIT_V(8); PG8_WAIT_L(0); PG8_BAR; PG8_MMA(0, 0, At, B0); PG8_MMA(0, 1, At, B1); PG8_BAR; PG8_SCHED;
;             PG8_LDA(At, 0, 1); PG8_STAGE(PG8_SB(0, 0), b2, voffB); PG8_STAGE(PG8_SB(0, 1), b2 + hstep, voffB); PG8_STAGE(PG8_SA(0, 0), a2, voffA);
.LBB0_283:
	s_ashr_i32 s15, s14, 31
	s_lshl_b64 s[16:17], s[14:15], 19
	s_add_u32 s16, s92, s16
	s_addc_u32 s17, s93, s17
	s_and_b64 s[18:19], s[6:7], exec
	s_cselect_b32 s15, s17, s21
	s_cselect_b32 s38, s16, s20
	s_ashr_i32 s13, s12, 31
	s_lshl_b64 s[18:19], s[12:13], 19
	s_add_u32 s18, s1, s18
	s_addc_u32 s19, s5, s19
	s_and_b64 s[24:25], s[6:7], exec
	s_cselect_b32 s13, s19, s23
	s_cselect_b32 s39, s18, s22
	s_add_u32 s20, s20, 0x40080
	s_addc_u32 s21, s21, 0
	s_add_u32 s40, s22, 0x100
	s_addc_u32 s41, s23, 0
	s_mov_b32 s42, -2
	s_add_u32 s22, s20, 0xfffc0080
	s_addc_u32 s23, s21, -1
	s_add_i32 s43, 0, 0x10000
	s_cmp_eq_u32 s42, 12
	s_cselect_b32 s25, s15, s23
	s_cselect_b32 s24, s38, s22
	v_add_u32_e32 v144, s43, v146
	s_cselect_b32 s23, s13, s41
	s_cselect_b32 s22, s39, s40
	s_add_i32 s46, 0, 0x14000
	ds_read_b128 v[150:153], v144
	ds_read_b128 v[172:175], v144 offset:1024
	ds_read_b128 v[176:179], v144 offset:2048
	ds_read_b128 v[180:183], v144 offset:3072
	v_add_u32_e32 v144, s46, v146
	ds_read_b128 v[184:187], v144
	ds_read_b128 v[188:191], v144 offset:1024
	ds_read_b128 v[192:195], v144 offset:2048
	ds_read_b128 v[196:199], v144 offset:3072
	v_lshl_add_u64 v[144:145], s[20:21], 0, v[138:139]
	s_add_i32 m0, s27, 0xc000
	ds_read_b128 v[200:203], v148
	ds_read_b128 v[204:207], v148 offset:1024
	ds_read_b128 v[208:211], v148 offset:2048
	ds_read_b128 v[212:215], v148 offset:3072
	ds_read_b128 v[216:219], v148 offset:4096
	ds_read_b128 v[220:223], v148 offset:5120
	ds_read_b128 v[224:227], v148 offset:6144
	ds_read_b128 v[228:231], v148 offset:7168
	global_load_lds_dwordx4 v[144:145], off
	v_lshl_add_u64 v[144:145], s[20:21], 0, v[140:141]
	s_add_i32 m0, s27, 0xe000
	s_nop 0
	global_load_lds_dwordx4 v[144:145], off
	s_waitcnt vmcnt(8)
	s_waitcnt lgkmcnt(0)
	s_barrier
	s_setprio 1
	s_waitcnt lgkmcnt(0)
	v_mfma_f32_16x16x32_bf16 v[126:129], v[150:153], v[200:203], 0
	v_mfma_f32_16x16x32_bf16 v[122:125], v[176:179], v[200:203], 0
	v_mfma_f32_16x16x32_bf16 v[110:113], v[150:153], v[208:211], 0
	v_mfma_f32_16x16x32_bf16 v[106:109], v[176:179], v[208:211], 0
	v_mfma_f32_16x16x32_bf16 v[94:97], v[150:153], v[216:219], 0
	v_mfma_f32_16x16x32_bf16 v[90:93], v[176:179], v[216:219], 0
	v_mfma_f32_16x16x32_bf16 v[78:81], v[150:153], v[224:227], 0
	v_mfma_f32_16x16x32_bf16 v[74:77], v[176:179], v[224:227], 0
	v_mfma_f32_16x16x32_bf16 v[126:129], v[172:175], v[204:207], v[126:129]
	v_mfma_f32_16x16x32_bf16 v[122:125], v[180:183], v[204:207], v[122:125]
	v_mfma_f32_16x16x32_bf16 v[110:113], v[172:175], v[212:215], v[110:113]
	v_mfma_f32_16x16x32_bf16 v[106:109], v[180:183], v[212:215], v[106:109]
	v_mfma_f32_16x16x32_bf16 v[94:97], v[172:175], v[220:223], v[94:97]
	v_mfma_f32_16x16x32_bf16 v[90:93], v[180:183], v[220:223], v[90:93]
	v_mfma_f32_16x16x32_bf16 v[78:81], v[172:175], v[228:231], v[78:81]
	v_mfma_f32_16x16x32_bf16 v[74:77], v[180:183], v[228:231], v[74:77]
	s_setprio 0
	s_setprio 1
	v_mfma_f32_16x16x32_bf16 v[118:121], v[184:187], v[200:203], 0
	v_mfma_f32_16x16x32_bf16 v[114:117], v[192:195], v[200:203], 0
	v_mfma_f32_16x16x32_bf16 v[102:105], v[184:187], v[208:211], 0
	v_mfma_f32_16x16x32_bf16 v[98:101], v[192:195], v[208:211], 0
	v_mfma_f32_16x16x32_bf16 v[86:89], v[184:187], v[216:219], 0
	v_mfma_f32_16x16x32_bf16 v[82:85], v[192:195], v[216:219], 0
	v_mfma_f32_16x16x32_bf16 v[70:73], v[184:187], v[224:227], 0
	v_mfma_f32_16x16x32_bf16 v[66:69], v[192:195], v[224:227], 0
	v_mfma_f32_16x16x32_bf16 v[118:121], v[188:191], v[204:207], v[118:121]
	v_mfma_f32_16x16x32_bf16 v[114:117], v[196:199], v[204:207], v[114:117]
	v_mfma_f32_16x16x32_bf16 v[102:105], v[188:191], v[212:215], v[102:105]
	v_mfma_f32_16x16x32_bf16 v[98:101], v[196:199], v[212:215], v[98:101]
	v_mfma_f32_16x16x32_bf16 v[86:89], v[188:191], v[220:223], v[86:89]
	v_mfma_f32_16x16x32_bf16 v[82:85], v[196:199], v[220:223], v[82:85]
	v_mfma_f32_16x16x32_bf16 v[70:73], v[188:191], v[228:231], v[70:73]
	v_mfma_f32_16x16x32_bf16 v[66:69], v[196:199], v[228:231], v[66:69]
	s_setprio 0
	s_barrier
	s_add_i32 s43, s43, s26
	v_lshl_add_u64 v[144:145], s[22:23], 0, v[134:135]
	s_mov_b32 m0, s43
	ds_read_b128 v[200:203], v148 offset:16384
	ds_read_b128 v[204:207], v148 offset:17408
	ds_read_b128 v[208:211], v148 offset:18432
	ds_read_b128 v[212:215], v148 offset:19456
	ds_read_b128 v[216:219], v148 offset:20480
	ds_read_b128 v[220:223], v148 offset:21504
	ds_read_b128 v[224:227], v148 offset:22528
	ds_read_b128 v[228:231], v148 offset:23552
	global_load_lds_dwordx4 v[144:145], off
	s_add_i32 m0, s43, 0x2000
	s_add_u32 s44, s22, 0x40000
	v_lshl_add_u64 v[232:233], s[22:23], 0, v[130:131]
	s_addc_u32 s45, s23, 0
	s_add_i32 s43, s46, s26
	global_load_lds_dwordx4 v[232:233], off
	v_lshl_add_u64 v[234:235], s[44:45], 0, v[134:135]
	s_mov_b32 m0, s43
	v_lshl_add_u64 v[236:237], s[24:25], 0, v[132:133]
	global_load_lds_dwordx4 v[234:235], off
	v_lshl_add_u64 v[234:235], s[44:45], 0, v[130:131]
	s_add_i32 m0, s43, 0x2000
	s_nop 0
	global_load_lds_dwordx4 v[234:235], off
	v_lshl_add_u64 v[234:235], s[24:25], 0, v[136:137]
	s_mov_b32 m0, s27
	s_nop 0
	global_load_lds_dwordx4 v[234:235], off
	s_mov_b32 m0, s28
	s_nop 0
	global_load_lds_dwordx4 v[236:237], off
	s_waitcnt vmcnt(8)
	s_waitcnt lgkmcnt(0)
	s_barrier
; #define PG8_STAGE(bufoff, gbase, voff) do { _Pragma("unroll") for (int _i = 0; _i < 2; ++_i) \
;         __builtin_amdgcn_global_load_lds((const unsigned*)((const char*)(gbase) + (voff)[_i]), (PG8_LAS unsigned*)(lds + (bufoff) + ldsw + _i * 8192), 16, 0, 0); } while (0)
; #define PG8_LDA(dst, b, h) do { _Pragma("unroll") for (int m = 0; m < 4; ++m) _Pragma("unroll") for (int k = 0; k < 2; ++k) dst[m][k] = *(const PG8_LAS bf16x8*)(lds + PG8_SA(b, h) + aoff + m * 2048 + k * 1024); } while (0)
; #define PG8_LDB(dst, b, h) do { _Pragma("unroll") for (int n = 0; n < 2; ++n) _Pragma("unroll") for (int k = 0; k < 2; ++k) dst[n][k] = *(const PG8_LAS bf16x8*)(lds + PG8_SB(b, h) + boff + n * 2048 + k * 1024); } while (0)
; #define PG8_MMA(ai, bj, At, Bt) do { __builtin_amdgcn_s_setprio(1); _Pragma("unroll") for (int m = 0; m < 4; ++m) _Pragma("unroll") for (int n = 0; n < 2; ++n) _Pragma("unroll") for (int k = 0; k < 2; ++k) \
;         acc[ai][bj][m][n] = __builtin_amdgcn_mfma_f32_16x16x32_bf16(Bt[n][k], At[m][k], acc[ai][bj][m][n], 0, 0, 0); __builtin_amdgcn_s_setprio(0); } while (0)
; #define PG8_WAIT_V(n) asm volatile("s_waitcnt vmcnt(" #n ")" ::: "memory")
; #define PG8_WAIT_L(n) asm volatile("s_waitcnt lgkmcnt(" #n ")" ::: "memory")
; #define PG8_BAR __builtin_amdgcn_s_barrier()
; #define PG8_SCHED __builtin_amdgcn_sched_barrier(0)
; template <class Epi, class Sched, bool ALIGN_EPI = false, bool SP2 = false>
; __device__ __forceinline__ void gemm_phase(PG8_LAS unsigned char* lds, const Gemm g, const Sched& S, const Epi& E) {
;     ...
;             PG8_WAIT_V(8); PG8_WAIT_L(0); PG8_BAR; PG8_MMA(0, 0, At, B0); PG8_MMA(0, 1, At, B1); PG8_BAR; PG8_SCHED;
;             PG8_LDA(At, 0, 1); PG8_STAGE(PG8_SB(0, 0), b2, voffB); PG8_STAGE(PG8_SB(0, 1), b2 + hstep, voffB); PG8_STAGE(PG8_SA(0, 0), a2, voffA);
;             PG8_WAIT_V(8); PG8_WAIT_L(0); PG8_BAR; PG8_MMA(1, 0, At, B0); PG8_MMA(1, 1, At, B1); PG8_BAR; PG8_SCHED;
;             PG8_LDB(B0, 1, 0); PG8_LDB(B1, 1, 1); PG8_SCHED; PG8_LDA(At, 1, 0); PG8_STAGE(PG8_SA(0, 1), a2 + hstep, voffA);
;             PG8_WAIT_V(8); PG8_WAIT_L(0); PG8_BAR; PG8_MMA(0, 0, At, B0); PG8_MMA(0, 1, At, B1); PG8_BAR; PG8_SCHED;
	s_setprio 1
	s_waitcnt lgkmcnt(0)
	v_mfma_f32_16x16x32_bf16 v[62:65], v[150:153], v[200:203], 0
	v_mfma_f32_16x16x32_bf16 v[58:61], v[176:179], v[200:203], 0
	v_mfma_f32_16x16x32_bf16 v[46:49], v[150:153], v[208:211], 0
	v_mfma_f32_16x16x32_bf16 v[42:45], v[176:179], v[208:211], 0
	v_mfma_f32_16x16x32_bf16 v[30:33], v[150:153], v[216:219], 0
	v_mfma_f32_16x16x32_bf16 v[26:29], v[176:179], v[216:219], 0
	v_mfma_f32_16x16x32_bf16 v[14:17], v[150:153], v[224:227], 0
	v_mfma_f32_16x16x32_bf16 v[10:13], v[176:179], v[224:227], 0
	v_mfma_f32_16x16x32_bf16 v[62:65], v[172:175], v[204:207], v[62:65]
	v_mfma_f32_16x16x32_bf16 v[58:61], v[180:183], v[204:207], v[58:61]
	v_mfma_f32_16x16x32_bf16 v[46:49], v[172:175], v[212:215], v[46:49]
	v_mfma_f32_16x16x32_bf16 v[42:45], v[180:183], v[212:215], v[42:45]
	v_mfma_f32_16x16x32_bf16 v[30:33], v[172:175], v[220:223], v[30:33]
	v_mfma_f32_16x16x32_bf16 v[26:29], v[180:183], v[220:223], v[26:29]
	v_mfma_f32_16x16x32_bf16 v[14:17], v[172:175], v[228:231], v[14:17]
	v_mfma_f32_16x16x32_bf16 v[10:13], v[180:183], v[228:231], v[10:13]
	s_setprio 0
	s_setprio 1
	v_mfma_f32_16x16x32_bf16 v[54:57], v[184:187], v[200:203], 0
	v_mfma_f32_16x16x32_bf16 v[50:53], v[192:195], v[200:203], 0
	v_mfma_f32_16x16x32_bf16 v[38:41], v[184:187], v[208:211], 0
	v_mfma_f32_16x16x32_bf16 v[34:37], v[192:195], v[208:211], 0
	v_mfma_f32_16x16x32_bf16 v[22:25], v[184:187], v[216:219], 0
	v_mfma_f32_16x16x32_bf16 v[18:21], v[192:195], v[216:219], 0
	v_mfma_f32_16x16x32_bf16 v[6:9], v[184:187], v[224:227], 0
	v_mfma_f32_16x16x32_bf16 v[2:5], v[192:195], v[224:227], 0
	v_mfma_f32_16x16x32_bf16 v[54:57], v[188:191], v[204:207], v[54:57]
	v_mfma_f32_16x16x32_bf16 v[50:53], v[196:199], v[204:207], v[50:53]
	v_mfma_f32_16x16x32_bf16 v[38:41], v[188:191], v[212:215], v[38:41]
	v_mfma_f32_16x16x32_bf16 v[34:37], v[196:199], v[212:215], v[34:37]
	v_mfma_f32_16x16x32_bf16 v[22:25], v[188:191], v[220:223], v[22:25]
	v_mfma_f32_16x16x32_bf16 v[18:21], v[196:199], v[220:223], v[18:21]
	v_mfma_f32_16x16x32_bf16 v[6:9], v[188:191], v[228:231], v[6:9]
	v_mfma_f32_16x16x32_bf16 v[2:5], v[196:199], v[228:231], v[2:5]
	s_setprio 0
	s_barrier
	s_add_i32 s43, 0, 0x18000
	v_add_u32_e32 v149, s43, v146
	s_add_i32 s44, 0, 0x1c000
	ds_read_b128 v[150:153], v149
	ds_read_b128 v[172:175], v149 offset:1024
	ds_read_b128 v[176:179], v149 offset:2048
	ds_read_b128 v[180:183], v149 offset:3072
	v_add_u32_e32 v149, s44, v146
	ds_read_b128 v[184:187], v149
	ds_read_b128 v[188:191], v149 offset:1024
	ds_read_b128 v[192:195], v149 offset:2048
	ds_read_b128 v[196:199], v149 offset:3072
	s_add_u32 s24, s24, 0x40000
	s_addc_u32 s25, s25, 0
	s_mov_b32 m0, s29
	v_lshl_add_u64 v[238:239], s[24:25], 0, v[136:137]
	ds_read_b128 v[200:203], v148 offset:32768
	ds_read_b128 v[204:207], v148 offset:33792
	ds_read_b128 v[208:211], v148 offset:34816
	ds_read_b128 v[212:215], v148 offset:35840
	ds_read_b128 v[216:219], v148 offset:36864
	ds_read_b128 v[220:223], v148 offset:37888
	ds_read_b128 v[224:227], v148 offset:38912
	ds_read_b128 v[228:231], v148 offset:39936
	global_load_lds_dwordx4 v[238:239], off
	v_lshl_add_u64 v[238:239], s[24:25], 0, v[132:133]
	s_mov_b32 m0, s30
	s_nop 0
	global_load_lds_dwordx4 v[238:239], off
	s_waitcnt vmcnt(8)
	s_waitcnt lgkmcnt(0)
	s_barrier
	s_setprio 1
	s_waitcnt lgkmcnt(0)
	v_mfma_f32_16x16x32_bf16 v[126:129], v[150:153], v[200:203], v[126:129]
	v_mfma_f32_16x16x32_bf16 v[122:125], v[176:179], v[200:203], v[122:125]
	v_mfma_f32_16x16x32_bf16 v[110:113], v[150:153], v[208:211], v[110:113]
	v_mfma_f32_16x16x32_bf16 v[106:109], v[176:179], v[208:211], v[106:109]
	v_mfma_f32_16x16x32_bf16 v[94:97], v[150:153], v[216:219], v[94:97]
	v_mfma_f32_16x16x32_bf16 v[90:93], v[176:179], v[216:219], v[90:93]
	v_mfma_f32_16x16x32_bf16 v[78:81], v[150:153], v[224:227], v[78:81]
	v_mfma_f32_16x16x32_bf16 v[74:77], v[176:179], v[224:227], v[74:77]
	v_mfma_f32_16x16x32_bf16 v[126:129], v[172:175], v[204:207], v[126:129]
	v_mfma_f32_16x16x32_bf16 v[122:125], v[180:183], v[204:207], v[122:125]
	v_mfma_f32_16x16x32_bf16 v[110:113], v[172:175], v[212:215], v[110:113]
	v_mfma_f32_16x16x32_bf16 v[106:109], v[180:183], v[212:215], v[106:109]
	v_mfma_f32_16x16x32_bf16 v[94:97], v[172:175], v[220:223], v[94:97]
	v_mfma_f32_16x16x32_bf16 v[90:93], v[180:183], v[220:223], v[90:93]
	v_mfma_f32_16x16x32_bf16 v[78:81], v[172:175], v[228:231], v[78:81]
	v_mfma_f32_16x16x32_bf16 v[74:77], v[180:183], v[228:231], v[74:77]
	s_setprio 0
	s_setprio 1
	v_mfma_f32_16x16x32_bf16 v[118:121], v[184:187], v[200:203], v[118:121]
	v_mfma_f32_16x16x32_bf16 v[114:117], v[192:195], v[200:203], v[114:117]
	v_mfma_f32_16x16x32_bf16 v[102:105], v[184:187], v[208:211], v[102:105]
	v_mfma_f32_16x16x32_bf16 v[98:101], v[192:195], v[208:211], v[98:101]
	v_mfma_f32_16x16x32_bf16 v[86:89], v[184:187], v[216:219], v[86:89]
	v_mfma_f32_16x16x32_bf16 v[82:85], v[192:195], v[216:219], v[82:85]
	v_mfma_f32_16x16x32_bf16 v[70:73], v[184:187], v[224:227], v[70:73]
	v_mfma_f32_16x16x32_bf16 v[66:69], v[192:195], v[224:227], v[66:69]
	v_mfma_f32_16x16x32_bf16 v[118:121], v[188:191], v[204:207], v[118:121]
	v_mfma_f32_16x16x32_bf16 v[114:117], v[196:199], v[204:207], v[114:117]
	v_mfma_f32_16x16x32_bf16 v[102:105], v[188:191], v[212:215], v[102:105]
	v_mfma_f32_16x16x32_bf16 v[98:101], v[196:199], v[212:215], v[98:101]
	v_mfma_f32_16x16x32_bf16 v[86:89], v[188:191], v[220:223], v[86:89]
	v_mfma_f32_16x16x32_bf16 v[82:85], v[196:199], v[220:223], v[82:85]
	v_mfma_f32_16x16x32_bf16 v[70:73], v[188:191], v[228:231], v[70:73]
	v_mfma_f32_16x16x32_bf16 v[66:69], v[196:199], v[228:231], v[66:69]
	s_setprio 0
	s_barrier
; #define PG8_STAGE(bufoff, gbase, voff) do { _Pragma("unroll") for (int _i = 0; _i < 2; ++_i) \
;         __builtin_amdgcn_global_load_lds((const unsigned*)((const char*)(gbase) + (voff)[_i]), (PG8_LAS unsigned*)(lds + (bufoff) + ldsw + _i * 8192), 16, 0, 0); } while (0)
; #define PG8_LDA(dst, b, h) do { _Pragma("unroll") for (int m = 0; m < 4; ++m) _Pragma("unroll") for (int k = 0; k < 2; ++k) dst[m][k] = *(const PG8_LAS bf16x8*)(lds + PG8_SA(b, h) + aoff + m * 2048 + k * 1024); } while (0)
; #define PG8_MMA(ai, bj, At, Bt) do { __builtin_amdgcn_s_setprio(1); _Pragma("unroll") for (int m = 0; m < 4; ++m) _Pragma("unroll") for (int n = 0; n < 2; ++n) _Pragma("unroll") for (int k = 0; k < 2; ++k) \
;         acc[ai][bj][m][n] = __builtin_amdgcn_mfma_f32_16x16x32_bf16(Bt[n][k], At[m][k], acc[ai][bj][m][n], 0, 0, 0); __builtin_amdgcn_s_setprio(0); } while (0)
; #define PG8_WAIT_V(n) asm volatile("s_waitcnt vmcnt(" #n ")" ::: "memory")
; #define PG8_WAIT_L(n) asm volatile("s_waitcnt lgkmcnt(" #n ")" ::: "memory")
; #define PG8_BAR __builtin_amdgcn_s_barrier()
; #define PG8_SCHED __builtin_amdgcn_sched_barrier(0)
; template <class Epi, class Sched, bool ALIGN_EPI = false, bool SP2 = false>
; __device__ __forceinline__ void gemm_phase(PG8_LAS unsigned char* lds, const Gemm g, const Sched& S, const Epi& E) {
;     ...
;             PG8_WAIT_V(8); PG8_WAIT_L(0); PG8_BAR; PG8_MMA(0, 0, At, B0); PG8_MMA(0, 1, At, B1); PG8_BAR; PG8_SCHED;
;             PG8_LDA(At, 1, 1); PG8_STAGE(PG8_SB(1, 0), b3, voffB); PG8_STAGE(PG8_SB(1, 1), b3 + hstep, voffB); PG8_STAGE(PG8_SA(1, 0), a3, voffA);
;             PG8_WAIT_V(8); PG8_WAIT_L(0); PG8_BAR; PG8_MMA(1, 0, At, B0); PG8_MMA(1, 1, At, B1); PG8_BAR; PG8_SCHED;
	s_add_i32 s24, s43, s26
	v_lshl_add_u64 v[144:145], v[144:145], 0, s[86:87]
	s_mov_b32 m0, s24
	ds_read_b128 v[200:203], v148 offset:49152
	ds_read_b128 v[204:207], v148 offset:50176
	ds_read_b128 v[208:211], v148 offset:51200
	ds_read_b128 v[212:215], v148 offset:52224
	ds_read_b128 v[216:219], v148 offset:53248
	ds_read_b128 v[220:223], v148 offset:54272
	ds_read_b128 v[224:227], v148 offset:55296
	ds_read_b128 v[228:231], v148 offset:56320
	global_load_lds_dwordx4 v[144:145], off
	s_add_i32 m0, s24, 0x2000
	s_add_u32 s22, s22, 0x40080
	v_lshl_add_u64 v[144:145], v[232:233], 0, s[86:87]
	s_addc_u32 s23, s23, 0
	s_add_i32 s24, s44, s26
	global_load_lds_dwordx4 v[144:145], off
	v_lshl_add_u64 v[144:145], s[22:23], 0, v[134:135]
	s_mov_b32 m0, s24
	s_nop 0
	global_load_lds_dwordx4 v[144:145], off
	v_lshl_add_u64 v[144:145], s[22:23], 0, v[130:131]
	s_add_i32 m0, s24, 0x2000
	s_nop 0
	global_load_lds_dwordx4 v[144:145], off
	v_lshl_add_u64 v[144:145], v[234:235], 0, s[86:87]
	s_mov_b32 m0, s31
	s_nop 0
	global_load_lds_dwordx4 v[144:145], off
	v_lshl_add_u64 v[144:145], v[236:237], 0, s[86:87]
	s_mov_b32 m0, s34
	s_nop 0
	global_load_lds_dwordx4 v[144:145], off
	s_waitcnt vmcnt(8)
	s_waitcnt lgkmcnt(0)
	s_barrier
	s_setprio 1
	s_waitcnt lgkmcnt(0)
	v_mfma_f32_16x16x32_bf16 v[62:65], v[150:153], v[200:203], v[62:65]
	v_mfma_f32_16x16x32_bf16 v[58:61], v[176:179], v[200:203], v[58:61]
	v_mfma_f32_16x16x32_bf16 v[46:49], v[150:153], v[208:211], v[46:49]
	v_mfma_f32_16x16x32_bf16 v[42:45], v[176:179], v[208:211], v[42:45]
	v_mfma_f32_16x16x32_bf16 v[30:33], v[150:153], v[216:219], v[30:33]
	v_mfma_f32_16x16x32_bf16 v[26:29], v[176:179], v[216:219], v[26:29]
	v_mfma_f32_16x16x32_bf16 v[14:17], v[150:153], v[224:227], v[14:17]
	v_mfma_f32_16x16x32_bf16 v[10:13], v[176:179], v[224:227], v[10:13]
	v_mfma_f32_16x16x32_bf16 v[62:65], v[172:175], v[204:207], v[62:65]
	v_mfma_f32_16x16x32_bf16 v[58:61], v[180:183], v[204:207], v[58:61]
	v_mfma_f32_16x16x32_bf16 v[46:49], v[172:175], v[212:215], v[46:49]
	v_mfma_f32_16x16x32_bf16 v[42:45], v[180:183], v[212:215], v[42:45]
	v_mfma_f32_16x16x32_bf16 v[30:33], v[172:175], v[220:223], v[30:33]
	v_mfma_f32_16x16x32_bf16 v[26:29], v[180:183], v[220:223], v[26:29]
	v_mfma_f32_16x16x32_bf16 v[14:17], v[172:175], v[228:231], v[14:17]
	v_mfma_f32_16x16x32_bf16 v[10:13], v[180:183], v[228:231], v[10:13]
	s_setprio 0
	s_setprio 1
	v_mfma_f32_16x16x32_bf16 v[54:57], v[184:187], v[200:203], v[54:57]
	v_mfma_f32_16x16x32_bf16 v[50:53], v[192:195], v[200:203], v[50:53]
	v_mfma_f32_16x16x32_bf16 v[38:41], v[184:187], v[208:211], v[38:41]
	v_mfma_f32_16x16x32_bf16 v[34:37], v[192:195], v[208:211], v[34:37]
	v_mfma_f32_16x16x32_bf16 v[22:25], v[184:187], v[216:219], v[22:25]
	v_mfma_f32_16x16x32_bf16 v[18:21], v[192:195], v[216:219], v[18:21]
	v_mfma_f32_16x16x32_bf16 v[6:9], v[184:187], v[224:227], v[6:9]
	v_mfma_f32_16x16x32_bf16 v[2:5], v[192:195], v[224:227], v[2:5]
	v_mfma_f32_16x16x32_bf16 v[54:57], v[188:191], v[204:207], v[54:57]
	v_mfma_f32_16x16x32_bf16 v[50:53], v[196:199], v[204:207], v[50:53]
	v_mfma_f32_16x16x32_bf16 v[38:41], v[188:191], v[212:215], v[38:41]
	v_mfma_f32_16x16x32_bf16 v[34:37], v[196:199], v[212:215], v[34:37]
	v_mfma_f32_16x16x32_bf16 v[22:25], v[188:191], v[220:223], v[22:25]
	v_mfma_f32_16x16x32_bf16 v[18:21], v[196:199], v[220:223], v[18:21]
	v_mfma_f32_16x16x32_bf16 v[6:9], v[188:191], v[228:231], v[6:9]
	v_mfma_f32_16x16x32_bf16 v[2:5], v[196:199], v[228:231], v[2:5]
	s_setprio 0
	s_barrier
	s_add_i32 s42, s42, 2
	s_add_u32 s20, s20, 0x100
	s_addc_u32 s21, s21, 0
	s_add_u32 s40, s40, 0x100
	s_addc_u32 s41, s41, 0
	s_cmp_gt_u32 s42, 13
	s_cbranch_scc1 .Lpeel_after_B

; #define PG8_BAR __builtin_amdgcn_s_barrier()
; template <class Epi, class Sched, bool ALIGN_EPI = false, bool SP2 = false>
; __device__ __forceinline__ void gemm_phase(PG8_LAS unsigned char* lds, const Gemm g, const Sched& S, const Epi& E) {
;     ...
;         }
;         if constexpr (ALIGN_EPI) { if (wr == 0) PG8_BAR; }
.Lpeel_after_B:
	s_and_b64 vcc, exec, s[10:11]
	s_cbranch_vccz .LBB0_287
	s_barrier
